# first K-tile of non-first GEMM units (up, in-proj) waits with vmcnt(26) so the 16 epilogue stores + 2 row-scale loads are not retired before the first MFMAs, on top of v062
# baseline (speedup 1.0000x reference)
; #define PG8_STAGE(bufoff, gbase, voff) do { _Pragma("unroll") for (int _i = 0; _i < 2; ++_i) \
;         __builtin_amdgcn_global_load_lds((const unsigned*)((const char*)(gbase) + (voff)[_i]), (PG8_LAS unsigned*)(lds + (bufoff) + ldsw + _i * 8192), 16, 0, 0); } while (0)
; #define PG8_WAIT_V(n) asm volatile("s_waitcnt vmcnt(" #n ")" ::: "memory")
; #define PG8_BAR __builtin_amdgcn_s_barrier()
; template <class Epi, class Sched, bool ALIGN_EPI = false, bool SP2 = false>
; __device__ __forceinline__ void gemm_phase(PG8_LAS unsigned char* lds, const Gemm g, const Sched& S, const Epi& E, int tid_in) {
;     ...
;     const int tid = tid_raw_, wid = __builtin_amdgcn_readfirstlane(tid >> 6), lane = tid & 63, wr = wid >> 2, wc = wid & 3, fr = lane & 15, fq = lane >> 4;
;     const int K = g.K, nt = K / BK;
;     unsigned voffA[2], voffB[2];
; #pragma unroll
;     for (int i = 0; i < 2; ++i) { int R, C; stage_rc(tid * 16 + i * 8192, R, C); const int Rb = Epi::PERM ? ((R & ~31) + perm32(R & 31)) : R;
;         voffA[i] = (unsigned)(R * K + C) * 2u; voffB[i] = (unsigned)(Rb * K + C) * 2u; }
;     const size_t kstep = (size_t)(BK * 2);
;     const size_t hstep = (size_t)HALF * K * 2;
;     const size_t tstep = 2 * hstep;
;     const unsigned ldsw = (unsigned)wid * 1024u;
;     const int aoff = lds_byte(wr * 64 + fr, fq * 8), boff = lds_byte(wc * 32 + fr, fq * 8);
;     ...
;         PG8_STAGE(PG8_SB(1, 0), cB + kstep, voffB); PG8_STAGE(PG8_SA(1, 0), cA + kstep, voffA); PG8_STAGE(PG8_SB(1, 1), cB + hstep + kstep, voffB);
;         PG8_WAIT_V(6); PG8_BAR;
.LBB0_180:
	s_waitcnt lgkmcnt(0)
	s_add_u32 s10, s10, 0xe800000
	s_addc_u32 s11, s11, 0
	s_add_u32 s73, s6, 0x300000
	s_addc_u32 s74, s7, 0
	s_add_u32 s12, s4, 0x310000
	s_addc_u32 s13, s5, 0
	s_and_b32 s6, s16, 3
	s_add_i32 m0, s49, 0x18000
	v_lshl_add_u64 v[8:9], v[8:9], 0, s[54:55]
	s_lshl_b32 s7, s17, 13
	s_lshl_b32 s18, s6, 12
	s_waitcnt vmcnt(2)
	s_barrier
	global_load_lds_dwordx4 v[8:9], off
	v_lshl_add_u64 v[6:7], v[6:7], 0, s[54:55]
	s_add_i32 m0, s49, 0x1a000
	s_add_i32 s75, s49, 0x8000
	s_add_i32 s76, s49, 0xa000
	global_load_lds_dwordx4 v[6:7], off
	v_lshl_add_u64 v[2:3], v[2:3], 0, s[54:55]
	s_mov_b32 m0, s75
	s_add_u32 s4, s28, 0x40080
	global_load_lds_dwordx4 v[2:3], off
	v_lshl_add_u64 v[2:3], v[4:5], 0, s[54:55]
	s_mov_b32 m0, s76
	s_addc_u32 s5, s29, 0
	global_load_lds_dwordx4 v[2:3], off
	s_add_i32 m0, s49, 0x1c000
	v_lshl_add_u64 v[2:3], s[4:5], 0, v[0:1]
	global_load_lds_dwordx4 v[2:3], off
	v_lshl_add_u64 v[2:3], s[4:5], 0, v[130:131]
	s_add_i32 m0, s49, 0x1e000
	s_cmpk_lt_u32 s15, 0x100
	global_load_lds_dwordx4 v[2:3], off
	v_bfe_u32 v3, v10, 4, 2
	v_and_b32_e32 v2, 15, v10
	v_lshlrev_b32_e32 v5, 4, v3
	v_lshl_or_b32 v156, s17, 6, v2
	v_lshl_or_b32 v5, v2, 6, v5
	v_or_b32_e32 v2, v3, v2
	v_cmp_eq_u32_e64 s[4:5], 0, v2
	v_lshlrev_b32_e32 v2, 14, v15
	v_and_b32_e32 v2, 0xffff8000, v2
	v_lshlrev_b32_e32 v4, 3, v3
	v_lshl_add_u32 v2, v14, 11, v2
	v_and_b32_e32 v3, 1, v15
	v_lshl_or_b32 v2, v3, 6, v2
	s_sext_i32_i8 s25, s14
	v_lshl_or_b32 v158, s6, 5, v4
	s_cselect_b64 s[14:15], -1, 0
	s_lshl_b32 s6, s16, 9
	v_lshl_add_u32 v136, v16, 1, v2
	v_lshlrev_b32_e32 v2, 14, v11
	v_lshlrev_b32_e32 v6, 2, v10
	s_and_b32 s6, s6, 0x200
	v_and_b32_e32 v2, 0xffff8000, v2
	v_and_b32_e32 v6, 32, v6
	s_waitcnt vmcnt(6)
	s_add_i32 s6, s6, s17
	v_lshl_add_u32 v2, v12, 11, v2
	v_and_b32_e32 v3, 1, v11
	v_bitop3_b32 v7, v5, s7, v6 bitop3:0xde
	s_bfe_u32 s78, s16, 0x10001
	s_lshl_b32 s81, s6, 2
	v_lshl_or_b32 v2, v3, 6, v2
	v_bitop3_b32 v157, v5, s18, v6 bitop3:0xde
	s_mov_b32 s77, 0
	s_or_b32 s79, s78, 8
	s_ashr_i32 s80, s35, 31
	s_addk_i32 s81, 0xe000
	v_mov_b32_e32 v137, v1
	v_lshl_add_u32 v138, v13, 1, v2
	v_mov_b32_e32 v139, v1
	v_add_u32_e32 v159, 0, v7
	s_barrier
	s_mov_b32 s101, 1
	s_branch .LBB0_183
.Lrelax_in_0:
	s_waitcnt vmcnt(26)
	s_branch .Lrelax_in_0_done

; #define PG8_BAR __builtin_amdgcn_s_barrier()
; template <class Epi, class Sched, bool ALIGN_EPI = false, bool SP2 = false>
; __device__ __forceinline__ void gemm_phase(PG8_LAS unsigned char* lds, const Gemm g, const Sched& S, const Epi& E, int tid_in) {
;     ...
;         if (!has_next) break;
; #pragma unroll
;         for (int a = 0; a < 2; ++a)
; #pragma unroll
;             for (int b = 0; b < 2; ++b)
; #pragma unroll
;                 for (int m = 0; m < 4; ++m)
; #pragma unroll
;                     for (int n = 0; n < 2; ++n) acc[a][b][m][n] = (f32x4){0.f, 0.f, 0.f, 0.f};
;         cur = nxt; cA = nA; cB = nB; ++ui;
;         if constexpr (ALIGN_EPI) { if (wr == 1) PG8_BAR; }
.LBB0_182:
	s_mov_b32 s101, -2
	s_andn2_b64 vcc, exec, s[6:7]
	s_mov_b32 s25, s16
	s_mov_b32 s24, s18
	s_mov_b64 s[28:29], s[22:23]
	s_mov_b64 s[26:27], s[20:21]
	s_cbranch_vccz .LBB0_202

; #define PG8_STAGE(bufoff, gbase, voff) do { _Pragma("unroll") for (int _i = 0; _i < 2; ++_i) \
;         __builtin_amdgcn_global_load_lds((const unsigned*)((const char*)(gbase) + (voff)[_i]), (PG8_LAS unsigned*)(lds + (bufoff) + ldsw + _i * 8192), 16, 0, 0); } while (0)
; #define PG8_LDA(dst, b, h) do { _Pragma("unroll") for (int m = 0; m < 4; ++m) _Pragma("unroll") for (int k = 0; k < 2; ++k) dst[m][k] = *(const PG8_LAS bf16x8*)(lds + PG8_SA(b, h) + aoff + m * 2048 + k * 1024); } while (0)
; #define PG8_LDB(dst, b, h) do { _Pragma("unroll") for (int n = 0; n < 2; ++n) _Pragma("unroll") for (int k = 0; k < 2; ++k) dst[n][k] = *(const PG8_LAS bf16x8*)(lds + PG8_SB(b, h) + boff + n * 2048 + k * 1024); } while (0)
; #define PG8_MMA(ai, bj, At, Bt) do { __builtin_amdgcn_s_setprio(1); _Pragma("unroll") for (int m = 0; m < 4; ++m) _Pragma("unroll") for (int n = 0; n < 2; ++n) _Pragma("unroll") for (int k = 0; k < 2; ++k) \
;         acc[ai][bj][m][n] = __builtin_amdgcn_mfma_f32_16x16x32_bf16(Bt[n][k], At[m][k], acc[ai][bj][m][n], 0, 0, 0); __builtin_amdgcn_s_setprio(0); } while (0)
; #define PG8_WAIT_V(n) asm volatile("s_waitcnt vmcnt(" #n ")" ::: "memory")
; #define PG8_WAIT_L(n) asm volatile("s_waitcnt lgkmcnt(" #n ")" ::: "memory")
; #define PG8_BAR __builtin_amdgcn_s_barrier()
; #define PG8_SCHED __builtin_amdgcn_sched_barrier(0)
; template <class Epi, class Sched, bool ALIGN_EPI = false, bool SP2 = false>
; __device__ __forceinline__ void gemm_phase(PG8_LAS unsigned char* lds, const Gemm g, const Sched& S, const Epi& E, int tid_in) {
;     ...
;             PG8_LDB(B0, 0, 0); PG8_LDB(B1, 0, 1); PG8_SCHED; PG8_LDA(At, 0, 0); PG8_STAGE(PG8_SA(1, 1), a1 + hstep, voffA);
;             PG8_WAIT_V(8); PG8_WAIT_L(0); PG8_BAR; PG8_MMA(0, 0, At, B0); PG8_MMA(0, 1, At, B1); PG8_BAR; PG8_SCHED;
;             PG8_LDA(At, 0, 1); PG8_STAGE(PG8_SB(0, 0), b2, voffB); PG8_STAGE(PG8_SB(0, 1), b2 + hstep, voffB); PG8_STAGE(PG8_SA(0, 0), a2, voffA);
;             PG8_WAIT_V(8); PG8_WAIT_L(0); PG8_BAR; PG8_MMA(1, 0, At, B0); PG8_MMA(1, 1, At, B1); PG8_BAR; PG8_SCHED;
.Lprio_skip_186:
.LBB0_186:
	s_add_u32 s28, s26, 0xfffc0080
	s_addc_u32 s29, s27, -1
	s_add_i32 s62, 0, 0x10000
	s_cmp_eq_u32 s85, 12
	s_cselect_b32 s31, s19, s29
	s_cselect_b32 s30, s46, s28
	v_add_u32_e32 v140, s62, v157
	s_cselect_b32 s29, s17, s84
	s_cselect_b32 s28, s82, s83
	s_add_i32 s86, 0, 0x14000
	ds_read_b128 v[142:145], v140
	ds_read_b128 v[146:149], v140 offset:1024
	ds_read_b128 v[150:153], v140 offset:2048
	ds_read_b128 v[160:163], v140 offset:3072
	v_add_u32_e32 v140, s86, v157
	ds_read_b128 v[164:167], v140
	ds_read_b128 v[168:171], v140 offset:1024
	ds_read_b128 v[172:175], v140 offset:2048
	ds_read_b128 v[176:179], v140 offset:3072
	v_lshl_add_u64 v[154:155], s[26:27], 0, v[136:137]
	s_add_i32 m0, s49, 0xc000
	ds_read_b128 v[180:183], v159
	ds_read_b128 v[184:187], v159 offset:1024
	ds_read_b128 v[196:199], v159 offset:2048
	ds_read_b128 v[228:231], v159 offset:3072
	ds_read_b128 v[232:235], v159 offset:4096
	ds_read_b128 v[236:239], v159 offset:5120
	ds_read_b128 v[240:243], v159 offset:6144
	ds_read_b128 v[244:247], v159 offset:7168
	global_load_lds_dwordx4 v[154:155], off
	v_lshl_add_u64 v[154:155], s[26:27], 0, v[138:139]
	s_add_i32 m0, s49, 0xe000
	s_nop 0
	global_load_lds_dwordx4 v[154:155], off
	s_cmp_eq_u32 s85, s101
	s_cbranch_scc1 .Lrelax_in_0
	s_waitcnt vmcnt(8)
.Lrelax_in_0_done:
	s_waitcnt lgkmcnt(0)
	s_barrier
	s_waitcnt lgkmcnt(0)
	v_mfma_f32_16x16x32_bf16 v[126:129], v[142:145], v[180:183], v[126:129]
	v_mfma_f32_16x16x32_bf16 v[122:125], v[150:153], v[180:183], v[122:125]
	v_mfma_f32_16x16x32_bf16 v[118:121], v[142:145], v[196:199], v[118:121]
	v_mfma_f32_16x16x32_bf16 v[114:117], v[150:153], v[196:199], v[114:117]
	v_mfma_f32_16x16x32_bf16 v[110:113], v[142:145], v[232:235], v[110:113]
	v_mfma_f32_16x16x32_bf16 v[106:109], v[150:153], v[232:235], v[106:109]
	v_mfma_f32_16x16x32_bf16 v[102:105], v[142:145], v[240:243], v[102:105]
	v_mfma_f32_16x16x32_bf16 v[98:101], v[150:153], v[240:243], v[98:101]
	v_mfma_f32_16x16x32_bf16 v[126:129], v[146:149], v[184:187], v[126:129]
	v_mfma_f32_16x16x32_bf16 v[122:125], v[160:163], v[184:187], v[122:125]
	v_mfma_f32_16x16x32_bf16 v[118:121], v[146:149], v[228:231], v[118:121]
	v_mfma_f32_16x16x32_bf16 v[114:117], v[160:163], v[228:231], v[114:117]
	v_mfma_f32_16x16x32_bf16 v[110:113], v[146:149], v[236:239], v[110:113]
	v_mfma_f32_16x16x32_bf16 v[106:109], v[160:163], v[236:239], v[106:109]
	v_mfma_f32_16x16x32_bf16 v[102:105], v[146:149], v[244:247], v[102:105]
	v_mfma_f32_16x16x32_bf16 v[98:101], v[160:163], v[244:247], v[98:101]
	v_mfma_f32_16x16x32_bf16 v[90:93], v[164:167], v[180:183], v[90:93]
	v_mfma_f32_16x16x32_bf16 v[82:85], v[172:175], v[180:183], v[82:85]
	v_mfma_f32_16x16x32_bf16 v[78:81], v[164:167], v[196:199], v[78:81]
	v_mfma_f32_16x16x32_bf16 v[74:77], v[172:175], v[196:199], v[74:77]
	v_mfma_f32_16x16x32_bf16 v[94:97], v[164:167], v[232:235], v[94:97]
	v_mfma_f32_16x16x32_bf16 v[86:89], v[172:175], v[232:235], v[86:89]
	v_mfma_f32_16x16x32_bf16 v[70:73], v[164:167], v[240:243], v[70:73]
	v_mfma_f32_16x16x32_bf16 v[66:69], v[172:175], v[240:243], v[66:69]
	v_mfma_f32_16x16x32_bf16 v[90:93], v[168:171], v[184:187], v[90:93]
	v_mfma_f32_16x16x32_bf16 v[82:85], v[176:179], v[184:187], v[82:85]
	v_mfma_f32_16x16x32_bf16 v[78:81], v[168:171], v[228:231], v[78:81]
	v_mfma_f32_16x16x32_bf16 v[74:77], v[176:179], v[228:231], v[74:77]
	v_mfma_f32_16x16x32_bf16 v[94:97], v[168:171], v[236:239], v[94:97]
	v_mfma_f32_16x16x32_bf16 v[86:89], v[176:179], v[236:239], v[86:89]
	v_mfma_f32_16x16x32_bf16 v[70:73], v[168:171], v[244:247], v[70:73]
	v_mfma_f32_16x16x32_bf16 v[66:69], v[176:179], v[244:247], v[66:69]
	s_barrier
	s_add_i32 s62, s62, s47
	v_lshl_add_u64 v[154:155], s[28:29], 0, v[0:1]
	s_mov_b32 m0, s62
	ds_read_b128 v[180:183], v159 offset:16384
	ds_read_b128 v[184:187], v159 offset:17408
	ds_read_b128 v[196:199], v159 offset:18432
	ds_read_b128 v[228:231], v159 offset:19456
	ds_read_b128 v[232:235], v159 offset:20480
	ds_read_b128 v[236:239], v159 offset:21504
	ds_read_b128 v[240:243], v159 offset:22528
	ds_read_b128 v[244:247], v159 offset:23552
	global_load_lds_dwordx4 v[154:155], off
	s_add_i32 m0, s62, 0x2000
	s_add_u32 s62, s28, 0x40000
	v_lshl_add_u64 v[248:249], s[28:29], 0, v[130:131]
	s_addc_u32 s63, s29, 0
	s_add_i32 s86, s86, s47
	global_load_lds_dwordx4 v[248:249], off
	v_lshl_add_u64 v[250:251], s[62:63], 0, v[0:1]
	s_mov_b32 m0, s86
	v_lshl_add_u64 v[252:253], s[30:31], 0, v[132:133]
	global_load_lds_dwordx4 v[250:251], off
	v_lshl_add_u64 v[250:251], s[62:63], 0, v[130:131]
	s_add_i32 m0, s86, 0x2000
	s_nop 0
	global_load_lds_dwordx4 v[250:251], off
	v_lshl_add_u64 v[250:251], s[30:31], 0, v[134:135]
	s_mov_b32 m0, s49
	s_nop 0
	global_load_lds_dwordx4 v[250:251], off
	s_mov_b32 m0, s70
	s_nop 0
	global_load_lds_dwordx4 v[252:253], off
	s_cmp_eq_u32 s85, s101
	s_cbranch_scc1 .Lrelax_in_1
	s_waitcnt vmcnt(8)
; #define PG8_STAGE(bufoff, gbase, voff) do { _Pragma("unroll") for (int _i = 0; _i < 2; ++_i) \
;         __builtin_amdgcn_global_load_lds((const unsigned*)((const char*)(gbase) + (voff)[_i]), (PG8_LAS unsigned*)(lds + (bufoff) + ldsw + _i * 8192), 16, 0, 0); } while (0)
; #define PG8_LDA(dst, b, h) do { _Pragma("unroll") for (int m = 0; m < 4; ++m) _Pragma("unroll") for (int k = 0; k < 2; ++k) dst[m][k] = *(const PG8_LAS bf16x8*)(lds + PG8_SA(b, h) + aoff + m * 2048 + k * 1024); } while (0)
; #define PG8_LDB(dst, b, h) do { _Pragma("unroll") for (int n = 0; n < 2; ++n) _Pragma("unroll") for (int k = 0; k < 2; ++k) dst[n][k] = *(const PG8_LAS bf16x8*)(lds + PG8_SB(b, h) + boff + n * 2048 + k * 1024); } while (0)
; #define PG8_MMA(ai, bj, At, Bt) do { __builtin_amdgcn_s_setprio(1); _Pragma("unroll") for (int m = 0; m < 4; ++m) _Pragma("unroll") for (int n = 0; n < 2; ++n) _Pragma("unroll") for (int k = 0; k < 2; ++k) \
;         acc[ai][bj][m][n] = __builtin_amdgcn_mfma_f32_16x16x32_bf16(Bt[n][k], At[m][k], acc[ai][bj][m][n], 0, 0, 0); __builtin_amdgcn_s_setprio(0); } while (0)
; #define PG8_WAIT_V(n) asm volatile("s_waitcnt vmcnt(" #n ")" ::: "memory")
; #define PG8_WAIT_L(n) asm volatile("s_waitcnt lgkmcnt(" #n ")" ::: "memory")
; #define PG8_BAR __builtin_amdgcn_s_barrier()
; #define PG8_SCHED __builtin_amdgcn_sched_barrier(0)
; template <class Epi, class Sched, bool ALIGN_EPI = false, bool SP2 = false>
; __device__ __forceinline__ void gemm_phase(PG8_LAS unsigned char* lds, const Gemm g, const Sched& S, const Epi& E, int tid_in) {
;     ...
;             PG8_WAIT_V(8); PG8_WAIT_L(0); PG8_BAR; PG8_MMA(1, 0, At, B0); PG8_MMA(1, 1, At, B1); PG8_BAR; PG8_SCHED;
;             PG8_LDB(B0, 1, 0); PG8_LDB(B1, 1, 1); PG8_SCHED; PG8_LDA(At, 1, 0); PG8_STAGE(PG8_SA(0, 1), a2 + hstep, voffA);
;             PG8_WAIT_V(8); PG8_WAIT_L(0); PG8_BAR; PG8_MMA(0, 0, At, B0); PG8_MMA(0, 1, At, B1); PG8_BAR; PG8_SCHED;
.Lrelax_in_1_done:
	s_waitcnt lgkmcnt(0)
	s_barrier
	s_waitcnt lgkmcnt(0)
	v_mfma_f32_16x16x32_bf16 v[62:65], v[142:145], v[180:183], v[62:65]
	v_mfma_f32_16x16x32_bf16 v[58:61], v[150:153], v[180:183], v[58:61]
	v_mfma_f32_16x16x32_bf16 v[54:57], v[142:145], v[196:199], v[54:57]
	v_mfma_f32_16x16x32_bf16 v[50:53], v[150:153], v[196:199], v[50:53]
	v_mfma_f32_16x16x32_bf16 v[46:49], v[142:145], v[232:235], v[46:49]
	v_mfma_f32_16x16x32_bf16 v[42:45], v[150:153], v[232:235], v[42:45]
	v_mfma_f32_16x16x32_bf16 v[38:41], v[142:145], v[240:243], v[38:41]
	v_mfma_f32_16x16x32_bf16 v[34:37], v[150:153], v[240:243], v[34:37]
	v_mfma_f32_16x16x32_bf16 v[62:65], v[146:149], v[184:187], v[62:65]
	v_mfma_f32_16x16x32_bf16 v[58:61], v[160:163], v[184:187], v[58:61]
	v_mfma_f32_16x16x32_bf16 v[54:57], v[146:149], v[228:231], v[54:57]
	v_mfma_f32_16x16x32_bf16 v[50:53], v[160:163], v[228:231], v[50:53]
	v_mfma_f32_16x16x32_bf16 v[46:49], v[146:149], v[236:239], v[46:49]
	v_mfma_f32_16x16x32_bf16 v[42:45], v[160:163], v[236:239], v[42:45]
	v_mfma_f32_16x16x32_bf16 v[38:41], v[146:149], v[244:247], v[38:41]
	v_mfma_f32_16x16x32_bf16 v[34:37], v[160:163], v[244:247], v[34:37]
	v_mfma_f32_16x16x32_bf16 v[26:29], v[164:167], v[180:183], v[26:29]
	v_mfma_f32_16x16x32_bf16 v[18:21], v[172:175], v[180:183], v[18:21]
	v_mfma_f32_16x16x32_bf16 v[14:17], v[164:167], v[196:199], v[14:17]
	v_mfma_f32_16x16x32_bf16 v[10:13], v[172:175], v[196:199], v[10:13]
	v_mfma_f32_16x16x32_bf16 v[30:33], v[164:167], v[232:235], v[30:33]
	v_mfma_f32_16x16x32_bf16 v[22:25], v[172:175], v[232:235], v[22:25]
	v_mfma_f32_16x16x32_bf16 v[6:9], v[164:167], v[240:243], v[6:9]
	v_mfma_f32_16x16x32_bf16 v[2:5], v[172:175], v[240:243], v[2:5]
	v_mfma_f32_16x16x32_bf16 v[26:29], v[168:171], v[184:187], v[26:29]
	v_mfma_f32_16x16x32_bf16 v[18:21], v[176:179], v[184:187], v[18:21]
	v_mfma_f32_16x16x32_bf16 v[14:17], v[168:171], v[228:231], v[14:17]
	v_mfma_f32_16x16x32_bf16 v[10:13], v[176:179], v[228:231], v[10:13]
	v_mfma_f32_16x16x32_bf16 v[30:33], v[168:171], v[236:239], v[30:33]
	v_mfma_f32_16x16x32_bf16 v[22:25], v[176:179], v[236:239], v[22:25]
	v_mfma_f32_16x16x32_bf16 v[6:9], v[168:171], v[244:247], v[6:9]
	v_mfma_f32_16x16x32_bf16 v[2:5], v[176:179], v[244:247], v[2:5]
	s_barrier
	s_add_i32 s62, 0, 0x18000
	v_add_u32_e32 v140, s62, v157
	s_add_i32 s63, 0, 0x1c000
	ds_read_b128 v[142:145], v140
	ds_read_b128 v[146:149], v140 offset:1024
	ds_read_b128 v[150:153], v140 offset:2048
	ds_read_b128 v[160:163], v140 offset:3072
	v_add_u32_e32 v140, s63, v157
	ds_read_b128 v[164:167], v140
	ds_read_b128 v[168:171], v140 offset:1024
	ds_read_b128 v[172:175], v140 offset:2048
	ds_read_b128 v[176:179], v140 offset:3072
	s_add_u32 s30, s30, 0x40000
	s_addc_u32 s31, s31, 0
	s_mov_b32 m0, s71
	v_lshl_add_u64 v[218:219], s[30:31], 0, v[134:135]
	ds_read_b128 v[180:183], v159 offset:32768
	ds_read_b128 v[184:187], v159 offset:33792
	ds_read_b128 v[196:199], v159 offset:34816
	ds_read_b128 v[228:231], v159 offset:35840
	ds_read_b128 v[232:235], v159 offset:36864
	ds_read_b128 v[236:239], v159 offset:37888
	ds_read_b128 v[240:243], v159 offset:38912
	ds_read_b128 v[244:247], v159 offset:39936
	global_load_lds_dwordx4 v[218:219], off
	v_lshl_add_u64 v[218:219], s[30:31], 0, v[132:133]
	s_mov_b32 m0, s72
	s_nop 0
	global_load_lds_dwordx4 v[218:219], off
	s_waitcnt vmcnt(8)
	s_waitcnt lgkmcnt(0)
	s_barrier
	s_waitcnt lgkmcnt(0)
	v_mfma_f32_16x16x32_bf16 v[126:129], v[142:145], v[180:183], v[126:129]
	v_mfma_f32_16x16x32_bf16 v[122:125], v[150:153], v[180:183], v[122:125]
	v_mfma_f32_16x16x32_bf16 v[118:121], v[142:145], v[196:199], v[118:121]
	v_mfma_f32_16x16x32_bf16 v[114:117], v[150:153], v[196:199], v[114:117]
	v_mfma_f32_16x16x32_bf16 v[110:113], v[142:145], v[232:235], v[110:113]
	v_mfma_f32_16x16x32_bf16 v[106:109], v[150:153], v[232:235], v[106:109]
	v_mfma_f32_16x16x32_bf16 v[102:105], v[142:145], v[240:243], v[102:105]
	v_mfma_f32_16x16x32_bf16 v[98:101], v[150:153], v[240:243], v[98:101]
	v_mfma_f32_16x16x32_bf16 v[126:129], v[146:149], v[184:187], v[126:129]
	v_mfma_f32_16x16x32_bf16 v[122:125], v[160:163], v[184:187], v[122:125]
	v_mfma_f32_16x16x32_bf16 v[118:121], v[146:149], v[228:231], v[118:121]
	v_mfma_f32_16x16x32_bf16 v[114:117], v[160:163], v[228:231], v[114:117]
	v_mfma_f32_16x16x32_bf16 v[110:113], v[146:149], v[236:239], v[110:113]
	v_mfma_f32_16x16x32_bf16 v[106:109], v[160:163], v[236:239], v[106:109]
	v_mfma_f32_16x16x32_bf16 v[102:105], v[146:149], v[244:247], v[102:105]
	v_mfma_f32_16x16x32_bf16 v[98:101], v[160:163], v[244:247], v[98:101]
	v_mfma_f32_16x16x32_bf16 v[90:93], v[164:167], v[180:183], v[90:93]
	v_mfma_f32_16x16x32_bf16 v[82:85], v[172:175], v[180:183], v[82:85]
	v_mfma_f32_16x16x32_bf16 v[78:81], v[164:167], v[196:199], v[78:81]
	v_mfma_f32_16x16x32_bf16 v[74:77], v[172:175], v[196:199], v[74:77]
	v_mfma_f32_16x16x32_bf16 v[94:97], v[164:167], v[232:235], v[94:97]
	v_mfma_f32_16x16x32_bf16 v[86:89], v[172:175], v[232:235], v[86:89]
	v_mfma_f32_16x16x32_bf16 v[70:73], v[164:167], v[240:243], v[70:73]
	v_mfma_f32_16x16x32_bf16 v[66:69], v[172:175], v[240:243], v[66:69]
	v_mfma_f32_16x16x32_bf16 v[90:93], v[168:171], v[184:187], v[90:93]
	v_mfma_f32_16x16x32_bf16 v[82:85], v[176:179], v[184:187], v[82:85]
	v_mfma_f32_16x16x32_bf16 v[78:81], v[168:171], v[228:231], v[78:81]
	v_mfma_f32_16x16x32_bf16 v[74:77], v[176:179], v[228:231], v[74:77]
	v_mfma_f32_16x16x32_bf16 v[94:97], v[168:171], v[236:239], v[94:97]
	v_mfma_f32_16x16x32_bf16 v[86:89], v[176:179], v[236:239], v[86:89]
	v_mfma_f32_16x16x32_bf16 v[70:73], v[168:171], v[244:247], v[70:73]
	v_mfma_f32_16x16x32_bf16 v[66:69], v[176:179], v[244:247], v[66:69]
	s_barrier
; #define PG8_STAGE(bufoff, gbase, voff) do { _Pragma("unroll") for (int _i = 0; _i < 2; ++_i) \
;         __builtin_amdgcn_global_load_lds((const unsigned*)((const char*)(gbase) + (voff)[_i]), (PG8_LAS unsigned*)(lds + (bufoff) + ldsw + _i * 8192), 16, 0, 0); } while (0)
; #define PG8_LDA(dst, b, h) do { _Pragma("unroll") for (int m = 0; m < 4; ++m) _Pragma("unroll") for (int k = 0; k < 2; ++k) dst[m][k] = *(const PG8_LAS bf16x8*)(lds + PG8_SA(b, h) + aoff + m * 2048 + k * 1024); } while (0)
; #define PG8_MMA(ai, bj, At, Bt) do { __builtin_amdgcn_s_setprio(1); _Pragma("unroll") for (int m = 0; m < 4; ++m) _Pragma("unroll") for (int n = 0; n < 2; ++n) _Pragma("unroll") for (int k = 0; k < 2; ++k) \
;         acc[ai][bj][m][n] = __builtin_amdgcn_mfma_f32_16x16x32_bf16(Bt[n][k], At[m][k], acc[ai][bj][m][n], 0, 0, 0); __builtin_amdgcn_s_setprio(0); } while (0)
; #define PG8_WAIT_V(n) asm volatile("s_waitcnt vmcnt(" #n ")" ::: "memory")
; #define PG8_WAIT_L(n) asm volatile("s_waitcnt lgkmcnt(" #n ")" ::: "memory")
; #define PG8_BAR __builtin_amdgcn_s_barrier()
; #define PG8_SCHED __builtin_amdgcn_sched_barrier(0)
; template <class Epi, class Sched, bool ALIGN_EPI = false, bool SP2 = false>
; __device__ __forceinline__ void gemm_phase(PG8_LAS unsigned char* lds, const Gemm g, const Sched& S, const Epi& E, int tid_in) {
;     ...
;             PG8_LDA(At, 1, 1); PG8_STAGE(PG8_SB(1, 0), b3, voffB); PG8_STAGE(PG8_SB(1, 1), b3 + hstep, voffB); PG8_STAGE(PG8_SA(1, 0), a3, voffA);
;             PG8_WAIT_V(8); PG8_WAIT_L(0); PG8_BAR; PG8_MMA(1, 0, At, B0); PG8_MMA(1, 1, At, B1); PG8_BAR; PG8_SCHED;
;     ...
;         }
;         if constexpr (ALIGN_EPI) { if (wr == 0) PG8_BAR; }
	s_add_i32 s30, s62, s47
	v_lshl_add_u64 v[154:155], v[154:155], 0, s[54:55]
	s_mov_b32 m0, s30
	ds_read_b128 v[180:183], v159 offset:49152
	ds_read_b128 v[184:187], v159 offset:50176
	ds_read_b128 v[196:199], v159 offset:51200
	ds_read_b128 v[228:231], v159 offset:52224
	ds_read_b128 v[232:235], v159 offset:53248
	ds_read_b128 v[236:239], v159 offset:54272
	ds_read_b128 v[240:243], v159 offset:55296
	ds_read_b128 v[244:247], v159 offset:56320
	global_load_lds_dwordx4 v[154:155], off
	s_add_i32 m0, s30, 0x2000
	s_add_u32 s28, s28, 0x40080
	v_lshl_add_u64 v[154:155], v[248:249], 0, s[54:55]
	s_addc_u32 s29, s29, 0
	s_add_i32 s30, s63, s47
	global_load_lds_dwordx4 v[154:155], off
	v_lshl_add_u64 v[154:155], s[28:29], 0, v[0:1]
	s_mov_b32 m0, s30
	s_nop 0
	global_load_lds_dwordx4 v[154:155], off
	v_lshl_add_u64 v[154:155], s[28:29], 0, v[130:131]
	s_add_i32 m0, s30, 0x2000
	s_nop 0
	global_load_lds_dwordx4 v[154:155], off
	v_lshl_add_u64 v[154:155], v[250:251], 0, s[54:55]
	s_mov_b32 m0, s75
	s_nop 0
	global_load_lds_dwordx4 v[154:155], off
	v_lshl_add_u64 v[154:155], v[252:253], 0, s[54:55]
	s_mov_b32 m0, s76
	s_nop 0
	global_load_lds_dwordx4 v[154:155], off
	s_waitcnt vmcnt(8)
	s_waitcnt lgkmcnt(0)
	s_barrier
	s_waitcnt lgkmcnt(0)
	v_mfma_f32_16x16x32_bf16 v[62:65], v[142:145], v[180:183], v[62:65]
	v_mfma_f32_16x16x32_bf16 v[58:61], v[150:153], v[180:183], v[58:61]
	v_mfma_f32_16x16x32_bf16 v[54:57], v[142:145], v[196:199], v[54:57]
	v_mfma_f32_16x16x32_bf16 v[50:53], v[150:153], v[196:199], v[50:53]
	v_mfma_f32_16x16x32_bf16 v[46:49], v[142:145], v[232:235], v[46:49]
	v_mfma_f32_16x16x32_bf16 v[42:45], v[150:153], v[232:235], v[42:45]
	v_mfma_f32_16x16x32_bf16 v[38:41], v[142:145], v[240:243], v[38:41]
	v_mfma_f32_16x16x32_bf16 v[34:37], v[150:153], v[240:243], v[34:37]
	v_mfma_f32_16x16x32_bf16 v[62:65], v[146:149], v[184:187], v[62:65]
	v_mfma_f32_16x16x32_bf16 v[58:61], v[160:163], v[184:187], v[58:61]
	v_mfma_f32_16x16x32_bf16 v[54:57], v[146:149], v[228:231], v[54:57]
	v_mfma_f32_16x16x32_bf16 v[50:53], v[160:163], v[228:231], v[50:53]
	v_mfma_f32_16x16x32_bf16 v[46:49], v[146:149], v[236:239], v[46:49]
	v_mfma_f32_16x16x32_bf16 v[42:45], v[160:163], v[236:239], v[42:45]
	v_mfma_f32_16x16x32_bf16 v[38:41], v[146:149], v[244:247], v[38:41]
	v_mfma_f32_16x16x32_bf16 v[34:37], v[160:163], v[244:247], v[34:37]
	v_mfma_f32_16x16x32_bf16 v[26:29], v[164:167], v[180:183], v[26:29]
	v_mfma_f32_16x16x32_bf16 v[18:21], v[172:175], v[180:183], v[18:21]
	v_mfma_f32_16x16x32_bf16 v[14:17], v[164:167], v[196:199], v[14:17]
	v_mfma_f32_16x16x32_bf16 v[10:13], v[172:175], v[196:199], v[10:13]
	v_mfma_f32_16x16x32_bf16 v[30:33], v[164:167], v[232:235], v[30:33]
	v_mfma_f32_16x16x32_bf16 v[22:25], v[172:175], v[232:235], v[22:25]
	v_mfma_f32_16x16x32_bf16 v[6:9], v[164:167], v[240:243], v[6:9]
	v_mfma_f32_16x16x32_bf16 v[2:5], v[172:175], v[240:243], v[2:5]
	v_mfma_f32_16x16x32_bf16 v[26:29], v[168:171], v[184:187], v[26:29]
	v_mfma_f32_16x16x32_bf16 v[18:21], v[176:179], v[184:187], v[18:21]
	v_mfma_f32_16x16x32_bf16 v[14:17], v[168:171], v[228:231], v[14:17]
	v_mfma_f32_16x16x32_bf16 v[10:13], v[176:179], v[228:231], v[10:13]
	v_mfma_f32_16x16x32_bf16 v[30:33], v[168:171], v[236:239], v[30:33]
	v_mfma_f32_16x16x32_bf16 v[22:25], v[176:179], v[236:239], v[22:25]
	v_mfma_f32_16x16x32_bf16 v[6:9], v[168:171], v[244:247], v[6:9]
	v_mfma_f32_16x16x32_bf16 v[2:5], v[176:179], v[244:247], v[2:5]
	s_barrier
	s_add_i32 s85, s85, 2
	s_add_u32 s26, s26, 0x100
	s_addc_u32 s27, s27, 0
	s_add_u32 s83, s83, 0x100
	s_addc_u32 s84, s84, 0
	s_cmp_gt_u32 s85, 13
	s_cbranch_scc0 .LBB0_186
	s_setprio 0
	s_and_b64 vcc, exec, s[14:15]
	s_cbranch_vccz .LBB0_189
	s_barrier

; #define PG8_STAGE(bufoff, gbase, voff) do { _Pragma("unroll") for (int _i = 0; _i < 2; ++_i) \
;         __builtin_amdgcn_global_load_lds((const unsigned*)((const char*)(gbase) + (voff)[_i]), (PG8_LAS unsigned*)(lds + (bufoff) + ldsw + _i * 8192), 16, 0, 0); } while (0)
; #define PG8_WAIT_V(n) asm volatile("s_waitcnt vmcnt(" #n ")" ::: "memory")
; #define PG8_BAR __builtin_amdgcn_s_barrier()
; template <class Epi, class Sched, bool ALIGN_EPI = false, bool SP2 = false>
; __device__ __forceinline__ void gemm_phase(PG8_LAS unsigned char* lds, const Gemm g, const Sched& S, const Epi& E, int tid_in) {
;     ...
;     const int tid = tid_raw_, wid = __builtin_amdgcn_readfirstlane(tid >> 6), lane = tid & 63, wr = wid >> 2, wc = wid & 3, fr = lane & 15, fq = lane >> 4;
;     const int K = g.K, nt = K / BK;
;     unsigned voffA[2], voffB[2];
; #pragma unroll
;     for (int i = 0; i < 2; ++i) { int R, C; stage_rc(tid * 16 + i * 8192, R, C); const int Rb = Epi::PERM ? ((R & ~31) + perm32(R & 31)) : R;
;         voffA[i] = (unsigned)(R * K + C) * 2u; voffB[i] = (unsigned)(Rb * K + C) * 2u; }
;     const size_t kstep = (size_t)(BK * 2);
;     const size_t hstep = (size_t)HALF * K * 2;
;     const size_t tstep = 2 * hstep;
;     const unsigned ldsw = (unsigned)wid * 1024u;
;     const int aoff = lds_byte(wr * 64 + fr, fq * 8), boff = lds_byte(wc * 32 + fr, fq * 8);
;     ...
;         PG8_STAGE(PG8_SB(1, 0), cB + kstep, voffB); PG8_STAGE(PG8_SA(1, 0), cA + kstep, voffA); PG8_STAGE(PG8_SB(1, 1), cB + hstep + kstep, voffB);
;         PG8_WAIT_V(6); PG8_BAR;
.LBB0_669:
	s_add_u32 s8, s8, 0xe800000
	v_lshrrev_b32_e32 v18, 1, v14
	s_addc_u32 s9, s9, 0
	v_and_b32_e32 v18, 24, v18
	s_sext_i32_i8 s23, s10
	s_add_u32 s10, s4, 0x310000
	v_and_b32_e32 v17, 15, v14
	v_lshlrev_b32_e32 v19, 1, v18
	v_lshlrev_b32_e32 v14, 2, v14
	s_addc_u32 s11, s5, 0
	v_lshl_or_b32 v144, s12, 6, v17
	v_lshl_or_b32 v17, v17, 6, v19
	s_lshl_b32 s4, s12, 13
	v_and_b32_e32 v14, 32, v14
	v_bitop3_b32 v19, v17, s4, v14 bitop3:0xde
	s_lshl_b32 s4, s13, 5
	s_and_b32 s14, s4, 0x60
	s_add_i32 m0, s47, 0x18000
	v_lshl_add_u64 v[8:9], v[8:9], 0, s[54:55]
	s_lshl_b32 s4, s14, 7
	s_waitcnt vmcnt(2)
	s_barrier
	global_load_lds_dwordx4 v[8:9], off
	v_lshl_add_u64 v[6:7], v[6:7], 0, s[54:55]
	s_add_i32 m0, s47, 0x1a000
	s_add_i32 s71, s47, 0x8000
	s_add_i32 s72, s47, 0xa000
	v_bitop3_b32 v145, v17, s4, v14 bitop3:0xde
	global_load_lds_dwordx4 v[6:7], off
	v_lshl_add_u64 v[2:3], v[2:3], 0, s[54:55]
	s_mov_b32 m0, s71
	s_add_u32 s4, s26, 0x40080
	global_load_lds_dwordx4 v[2:3], off
	v_lshl_add_u64 v[2:3], v[4:5], 0, s[54:55]
	s_mov_b32 m0, s72
	s_addc_u32 s5, s27, 0
	global_load_lds_dwordx4 v[2:3], off
	s_add_i32 m0, s47, 0x1c000
	v_lshl_add_u64 v[2:3], s[4:5], 0, v[0:1]
	global_load_lds_dwordx4 v[2:3], off
	v_lshl_add_u64 v[2:3], s[4:5], 0, v[134:135]
	s_add_i32 m0, s47, 0x1e000
	s_cmpk_lt_u32 s16, 0x100
	global_load_lds_dwordx4 v[2:3], off
	v_lshlrev_b32_e32 v2, 14, v10
	v_and_b32_e32 v2, 0xffff8000, v2
	v_lshl_add_u32 v2, v11, 11, v2
	v_and_b32_e32 v3, 1, v10
	v_lshl_or_b32 v2, v3, 6, v2
	v_lshl_add_u32 v136, v12, 1, v2
	v_lshlrev_b32_e32 v2, 14, v13
	v_and_b32_e32 v2, 0xffff8000, v2
	s_waitcnt vmcnt(6)
	v_lshl_add_u32 v2, v15, 11, v2
	v_and_b32_e32 v3, 1, v13
	v_lshl_or_b32 v2, v3, 6, v2
	s_cselect_b64 s[12:13], -1, 0
	s_ashr_i32 s73, s2, 31
	v_or_b32_e32 v146, s14, v18
	v_mov_b32_e32 v137, v1
	v_lshl_add_u32 v138, v16, 1, v2
	v_mov_b32_e32 v139, v1
	s_mov_b32 s74, 0
	v_add_u32_e32 v147, 0, v19
	s_barrier
	s_mov_b32 s101, 1
	s_branch .LBB0_672

; #define PG8_BAR __builtin_amdgcn_s_barrier()
; template <class Epi, class Sched, bool ALIGN_EPI = false, bool SP2 = false>
; __device__ __forceinline__ void gemm_phase(PG8_LAS unsigned char* lds, const Gemm g, const Sched& S, const Epi& E, int tid_in) {
;     ...
;         if (!has_next) break;
; #pragma unroll
;         for (int a = 0; a < 2; ++a)
; #pragma unroll
;             for (int b = 0; b < 2; ++b)
; #pragma unroll
;                 for (int m = 0; m < 4; ++m)
; #pragma unroll
;                     for (int n = 0; n < 2; ++n) acc[a][b][m][n] = (f32x4){0.f, 0.f, 0.f, 0.f};
;         cur = nxt; cA = nA; cB = nB; ++ui;
;         if constexpr (ALIGN_EPI) { if (wr == 1) PG8_BAR; }
.LBB0_671:
	s_mov_b32 s101, -2
	s_andn2_b64 vcc, exec, s[22:23]
	s_mov_b32 s23, s14
	s_mov_b32 s22, s16
	s_mov_b64 s[26:27], s[20:21]
	s_mov_b64 s[24:25], s[18:19]
	s_cbranch_vccz .LBB0_685

; #define PG8_STAGE(bufoff, gbase, voff) do { _Pragma("unroll") for (int _i = 0; _i < 2; ++_i) \
;         __builtin_amdgcn_global_load_lds((const unsigned*)((const char*)(gbase) + (voff)[_i]), (PG8_LAS unsigned*)(lds + (bufoff) + ldsw + _i * 8192), 16, 0, 0); } while (0)
; #define PG8_LDA(dst, b, h) do { _Pragma("unroll") for (int m = 0; m < 4; ++m) _Pragma("unroll") for (int k = 0; k < 2; ++k) dst[m][k] = *(const PG8_LAS bf16x8*)(lds + PG8_SA(b, h) + aoff + m * 2048 + k * 1024); } while (0)
; #define PG8_LDB(dst, b, h) do { _Pragma("unroll") for (int n = 0; n < 2; ++n) _Pragma("unroll") for (int k = 0; k < 2; ++k) dst[n][k] = *(const PG8_LAS bf16x8*)(lds + PG8_SB(b, h) + boff + n * 2048 + k * 1024); } while (0)
; #define PG8_MMA(ai, bj, At, Bt) do { __builtin_amdgcn_s_setprio(1); _Pragma("unroll") for (int m = 0; m < 4; ++m) _Pragma("unroll") for (int n = 0; n < 2; ++n) _Pragma("unroll") for (int k = 0; k < 2; ++k) \
;         acc[ai][bj][m][n] = __builtin_amdgcn_mfma_f32_16x16x32_bf16(Bt[n][k], At[m][k], acc[ai][bj][m][n], 0, 0, 0); __builtin_amdgcn_s_setprio(0); } while (0)
; #define PG8_WAIT_V(n) asm volatile("s_waitcnt vmcnt(" #n ")" ::: "memory")
; #define PG8_WAIT_L(n) asm volatile("s_waitcnt lgkmcnt(" #n ")" ::: "memory")
; #define PG8_BAR __builtin_amdgcn_s_barrier()
; #define PG8_SCHED __builtin_amdgcn_sched_barrier(0)
; template <class Epi, class Sched, bool ALIGN_EPI = false, bool SP2 = false>
; __device__ __forceinline__ void gemm_phase(PG8_LAS unsigned char* lds, const Gemm g, const Sched& S, const Epi& E, int tid_in) {
;     ...
;         for (int t = 0; t < nt; t += 2) {
;             const bool last = (t == nt - 2);
;             const char* a1 = cA + (size_t)(t + 1) * kstep;
;             const char* a2 = last ? nA : cA + (size_t)(t + 2) * kstep; const char* b2 = last ? nB : cB + (size_t)(t + 2) * kstep;
;             const char* a3 = a2 + kstep; const char* b3 = b2 + kstep;
;             if (last && has_next) S.a_ready(nxt);
;             if constexpr (SP2) {
;             PG8_LDB(B0, 0, 0); PG8_LDB(B1, 0, 1); PG8_SCHED; PG8_LDA(At, 0, 0); PG8_STAGE(PG8_SA(1, 1), a1 + hstep, voffA);
;             PG8_WAIT_V(8); PG8_WAIT_L(0); PG8_BAR; PG8_MMA(0, 0, At, B0); PG8_MMA(0, 1, At, B1); PG8_BAR; PG8_SCHED;
;             PG8_LDA(At, 0, 1); PG8_STAGE(PG8_SB(0, 0), b2, voffB); PG8_STAGE(PG8_SB(0, 1), b2 + hstep, voffB); PG8_STAGE(PG8_SA(0, 0), a2, voffA);
.Lprio_skip_679:
.LBB0_679:
	s_add_u32 s26, s24, 0xfffc0080
	s_addc_u32 s27, s25, -1
	s_add_i32 s62, 0, 0x10000
	s_cmp_eq_u32 s78, 12
	s_cselect_b32 s29, s17, s27
	s_cselect_b32 s28, s46, s26
	s_cselect_b32 s27, s15, s77
	s_cselect_b32 s26, s75, s76
	s_add_i32 s79, 0, 0x14000
	v_add_u32_e32 v156, s62, v145
	v_add_u32_e32 v172, s79, v145
	ds_read_b128 v[140:143], v156
	ds_read_b128 v[148:151], v156 offset:1024
	ds_read_b128 v[152:155], v156 offset:2048
	ds_read_b128 v[156:159], v156 offset:3072
	ds_read_b128 v[160:163], v172
	ds_read_b128 v[164:167], v172 offset:1024
	ds_read_b128 v[168:171], v172 offset:2048
	ds_read_b128 v[172:175], v172 offset:3072
	v_lshl_add_u64 v[218:219], s[24:25], 0, v[136:137]
	s_add_i32 m0, s47, 0xc000
	ds_read_b128 v[176:179], v147
	ds_read_b128 v[180:183], v147 offset:1024
	ds_read_b128 v[184:187], v147 offset:2048
	ds_read_b128 v[196:199], v147 offset:3072
	ds_read_b128 v[228:231], v147 offset:4096
	ds_read_b128 v[232:235], v147 offset:5120
	ds_read_b128 v[236:239], v147 offset:6144
	ds_read_b128 v[240:243], v147 offset:7168
	global_load_lds_dwordx4 v[218:219], off
	v_lshl_add_u64 v[218:219], s[24:25], 0, v[138:139]
	s_add_i32 m0, s47, 0xe000
	s_nop 0
	global_load_lds_dwordx4 v[218:219], off
	s_cmp_eq_u32 s78, s101
	s_cbranch_scc1 .Lrelax_up_0
	s_waitcnt vmcnt(8)
.Lrelax_up_0_done:
	s_waitcnt lgkmcnt(0)
	s_barrier
	s_waitcnt lgkmcnt(0)
	v_mfma_f32_16x16x32_bf16 v[126:129], v[140:143], v[176:179], v[126:129]
	v_mfma_f32_16x16x32_bf16 v[122:125], v[152:155], v[176:179], v[122:125]
	v_mfma_f32_16x16x32_bf16 v[110:113], v[140:143], v[184:187], v[110:113]
	v_mfma_f32_16x16x32_bf16 v[106:109], v[152:155], v[184:187], v[106:109]
	v_mfma_f32_16x16x32_bf16 v[94:97], v[140:143], v[228:231], v[94:97]
	v_mfma_f32_16x16x32_bf16 v[90:93], v[152:155], v[228:231], v[90:93]
	v_mfma_f32_16x16x32_bf16 v[78:81], v[140:143], v[236:239], v[78:81]
	v_mfma_f32_16x16x32_bf16 v[74:77], v[152:155], v[236:239], v[74:77]
	v_mfma_f32_16x16x32_bf16 v[126:129], v[148:151], v[180:183], v[126:129]
	v_mfma_f32_16x16x32_bf16 v[122:125], v[156:159], v[180:183], v[122:125]
	v_mfma_f32_16x16x32_bf16 v[110:113], v[148:151], v[196:199], v[110:113]
	v_mfma_f32_16x16x32_bf16 v[106:109], v[156:159], v[196:199], v[106:109]
	v_mfma_f32_16x16x32_bf16 v[94:97], v[148:151], v[232:235], v[94:97]
	v_mfma_f32_16x16x32_bf16 v[90:93], v[156:159], v[232:235], v[90:93]
	v_mfma_f32_16x16x32_bf16 v[78:81], v[148:151], v[240:243], v[78:81]
	v_mfma_f32_16x16x32_bf16 v[74:77], v[156:159], v[240:243], v[74:77]
	v_mfma_f32_16x16x32_bf16 v[118:121], v[160:163], v[176:179], v[118:121]
	v_mfma_f32_16x16x32_bf16 v[114:117], v[168:171], v[176:179], v[114:117]
	v_mfma_f32_16x16x32_bf16 v[102:105], v[160:163], v[184:187], v[102:105]
	v_mfma_f32_16x16x32_bf16 v[98:101], v[168:171], v[184:187], v[98:101]
	v_mfma_f32_16x16x32_bf16 v[86:89], v[160:163], v[228:231], v[86:89]
	v_mfma_f32_16x16x32_bf16 v[82:85], v[168:171], v[228:231], v[82:85]
	v_mfma_f32_16x16x32_bf16 v[70:73], v[160:163], v[236:239], v[70:73]
	v_mfma_f32_16x16x32_bf16 v[66:69], v[168:171], v[236:239], v[66:69]
	v_mfma_f32_16x16x32_bf16 v[118:121], v[164:167], v[180:183], v[118:121]
	v_mfma_f32_16x16x32_bf16 v[114:117], v[172:175], v[180:183], v[114:117]
	v_mfma_f32_16x16x32_bf16 v[102:105], v[164:167], v[196:199], v[102:105]
	v_mfma_f32_16x16x32_bf16 v[98:101], v[172:175], v[196:199], v[98:101]
	v_mfma_f32_16x16x32_bf16 v[86:89], v[164:167], v[232:235], v[86:89]
	v_mfma_f32_16x16x32_bf16 v[82:85], v[172:175], v[232:235], v[82:85]
	v_mfma_f32_16x16x32_bf16 v[70:73], v[164:167], v[240:243], v[70:73]
	v_mfma_f32_16x16x32_bf16 v[66:69], v[172:175], v[240:243], v[66:69]
	s_barrier
	s_add_i32 s62, s62, s41
	v_lshl_add_u64 v[218:219], s[26:27], 0, v[0:1]
	s_mov_b32 m0, s62
	ds_read_b128 v[176:179], v147 offset:16384
	ds_read_b128 v[180:183], v147 offset:17408
	ds_read_b128 v[184:187], v147 offset:18432
	ds_read_b128 v[196:199], v147 offset:19456
	ds_read_b128 v[228:231], v147 offset:20480
	ds_read_b128 v[232:235], v147 offset:21504
	ds_read_b128 v[236:239], v147 offset:22528
	ds_read_b128 v[240:243], v147 offset:23552
	global_load_lds_dwordx4 v[218:219], off
	s_add_i32 m0, s62, 0x2000
	s_add_u32 s62, s26, 0x40000
	v_lshl_add_u64 v[244:245], s[26:27], 0, v[134:135]
	s_addc_u32 s63, s27, 0
	s_add_i32 s79, s79, s41
	global_load_lds_dwordx4 v[244:245], off
	v_lshl_add_u64 v[246:247], s[62:63], 0, v[0:1]
	s_mov_b32 m0, s79
	v_lshl_add_u64 v[248:249], s[28:29], 0, v[132:133]
	global_load_lds_dwordx4 v[246:247], off
	v_lshl_add_u64 v[246:247], s[62:63], 0, v[134:135]
	s_add_i32 m0, s79, 0x2000
	s_nop 0
	global_load_lds_dwordx4 v[246:247], off
	v_lshl_add_u64 v[246:247], s[28:29], 0, v[130:131]
	s_mov_b32 m0, s47
	s_nop 0
	global_load_lds_dwordx4 v[246:247], off
	s_mov_b32 m0, s48
	s_nop 0
	global_load_lds_dwordx4 v[248:249], off
	s_cmp_eq_u32 s78, s101
	s_cbranch_scc1 .Lrelax_up_1
	s_waitcnt vmcnt(8)
; #define PG8_STAGE(bufoff, gbase, voff) do { _Pragma("unroll") for (int _i = 0; _i < 2; ++_i) \
;         __builtin_amdgcn_global_load_lds((const unsigned*)((const char*)(gbase) + (voff)[_i]), (PG8_LAS unsigned*)(lds + (bufoff) + ldsw + _i * 8192), 16, 0, 0); } while (0)
; #define PG8_LDA(dst, b, h) do { _Pragma("unroll") for (int m = 0; m < 4; ++m) _Pragma("unroll") for (int k = 0; k < 2; ++k) dst[m][k] = *(const PG8_LAS bf16x8*)(lds + PG8_SA(b, h) + aoff + m * 2048 + k * 1024); } while (0)
; #define PG8_LDB(dst, b, h) do { _Pragma("unroll") for (int n = 0; n < 2; ++n) _Pragma("unroll") for (int k = 0; k < 2; ++k) dst[n][k] = *(const PG8_LAS bf16x8*)(lds + PG8_SB(b, h) + boff + n * 2048 + k * 1024); } while (0)
; #define PG8_MMA(ai, bj, At, Bt) do { __builtin_amdgcn_s_setprio(1); _Pragma("unroll") for (int m = 0; m < 4; ++m) _Pragma("unroll") for (int n = 0; n < 2; ++n) _Pragma("unroll") for (int k = 0; k < 2; ++k) \
;         acc[ai][bj][m][n] = __builtin_amdgcn_mfma_f32_16x16x32_bf16(Bt[n][k], At[m][k], acc[ai][bj][m][n], 0, 0, 0); __builtin_amdgcn_s_setprio(0); } while (0)
; #define PG8_WAIT_V(n) asm volatile("s_waitcnt vmcnt(" #n ")" ::: "memory")
; #define PG8_WAIT_L(n) asm volatile("s_waitcnt lgkmcnt(" #n ")" ::: "memory")
; #define PG8_BAR __builtin_amdgcn_s_barrier()
; #define PG8_SCHED __builtin_amdgcn_sched_barrier(0)
; template <class Epi, class Sched, bool ALIGN_EPI = false, bool SP2 = false>
; __device__ __forceinline__ void gemm_phase(PG8_LAS unsigned char* lds, const Gemm g, const Sched& S, const Epi& E, int tid_in) {
;     ...
;             PG8_WAIT_V(8); PG8_WAIT_L(0); PG8_BAR; PG8_MMA(1, 0, At, B0); PG8_MMA(1, 1, At, B1); PG8_BAR; PG8_SCHED;
;             PG8_LDB(B0, 1, 0); PG8_LDB(B1, 1, 1); PG8_SCHED; PG8_LDA(At, 1, 0); PG8_STAGE(PG8_SA(0, 1), a2 + hstep, voffA);
;             PG8_WAIT_V(8); PG8_WAIT_L(0); PG8_BAR; PG8_MMA(0, 0, At, B0); PG8_MMA(0, 1, At, B1); PG8_BAR; PG8_SCHED;
.Lrelax_up_1_done:
	s_waitcnt lgkmcnt(0)
	s_barrier
	s_waitcnt lgkmcnt(0)
	v_mfma_f32_16x16x32_bf16 v[62:65], v[140:143], v[176:179], v[62:65]
	v_mfma_f32_16x16x32_bf16 v[58:61], v[152:155], v[176:179], v[58:61]
	v_mfma_f32_16x16x32_bf16 v[46:49], v[140:143], v[184:187], v[46:49]
	v_mfma_f32_16x16x32_bf16 v[42:45], v[152:155], v[184:187], v[42:45]
	v_mfma_f32_16x16x32_bf16 v[30:33], v[140:143], v[228:231], v[30:33]
	v_mfma_f32_16x16x32_bf16 v[26:29], v[152:155], v[228:231], v[26:29]
	v_mfma_f32_16x16x32_bf16 v[14:17], v[140:143], v[236:239], v[14:17]
	v_mfma_f32_16x16x32_bf16 v[10:13], v[152:155], v[236:239], v[10:13]
	v_mfma_f32_16x16x32_bf16 v[62:65], v[148:151], v[180:183], v[62:65]
	v_mfma_f32_16x16x32_bf16 v[58:61], v[156:159], v[180:183], v[58:61]
	v_mfma_f32_16x16x32_bf16 v[46:49], v[148:151], v[196:199], v[46:49]
	v_mfma_f32_16x16x32_bf16 v[42:45], v[156:159], v[196:199], v[42:45]
	v_mfma_f32_16x16x32_bf16 v[30:33], v[148:151], v[232:235], v[30:33]
	v_mfma_f32_16x16x32_bf16 v[26:29], v[156:159], v[232:235], v[26:29]
	v_mfma_f32_16x16x32_bf16 v[14:17], v[148:151], v[240:243], v[14:17]
	v_mfma_f32_16x16x32_bf16 v[10:13], v[156:159], v[240:243], v[10:13]
	v_mfma_f32_16x16x32_bf16 v[54:57], v[160:163], v[176:179], v[54:57]
	v_mfma_f32_16x16x32_bf16 v[50:53], v[168:171], v[176:179], v[50:53]
	v_mfma_f32_16x16x32_bf16 v[38:41], v[160:163], v[184:187], v[38:41]
	v_mfma_f32_16x16x32_bf16 v[34:37], v[168:171], v[184:187], v[34:37]
	v_mfma_f32_16x16x32_bf16 v[22:25], v[160:163], v[228:231], v[22:25]
	v_mfma_f32_16x16x32_bf16 v[18:21], v[168:171], v[228:231], v[18:21]
	v_mfma_f32_16x16x32_bf16 v[6:9], v[160:163], v[236:239], v[6:9]
	v_mfma_f32_16x16x32_bf16 v[2:5], v[168:171], v[236:239], v[2:5]
	v_mfma_f32_16x16x32_bf16 v[54:57], v[164:167], v[180:183], v[54:57]
	v_mfma_f32_16x16x32_bf16 v[50:53], v[172:175], v[180:183], v[50:53]
	v_mfma_f32_16x16x32_bf16 v[38:41], v[164:167], v[196:199], v[38:41]
	v_mfma_f32_16x16x32_bf16 v[34:37], v[172:175], v[196:199], v[34:37]
	v_mfma_f32_16x16x32_bf16 v[22:25], v[164:167], v[232:235], v[22:25]
	v_mfma_f32_16x16x32_bf16 v[18:21], v[172:175], v[232:235], v[18:21]
	v_mfma_f32_16x16x32_bf16 v[6:9], v[164:167], v[240:243], v[6:9]
	v_mfma_f32_16x16x32_bf16 v[2:5], v[172:175], v[240:243], v[2:5]
	s_barrier
	s_add_i32 s62, 0, 0x18000
	s_add_i32 s63, 0, 0x1c000
	v_add_u32_e32 v156, s62, v145
	v_add_u32_e32 v172, s63, v145
	ds_read_b128 v[140:143], v156
	ds_read_b128 v[148:151], v156 offset:1024
	ds_read_b128 v[152:155], v156 offset:2048
	ds_read_b128 v[156:159], v156 offset:3072
	ds_read_b128 v[160:163], v172
	ds_read_b128 v[164:167], v172 offset:1024
	ds_read_b128 v[168:171], v172 offset:2048
	ds_read_b128 v[172:175], v172 offset:3072
	s_add_u32 s28, s28, 0x40000
	s_addc_u32 s29, s29, 0
	s_mov_b32 m0, s49
	v_lshl_add_u64 v[250:251], s[28:29], 0, v[130:131]
	ds_read_b128 v[176:179], v147 offset:32768
	ds_read_b128 v[180:183], v147 offset:33792
	ds_read_b128 v[184:187], v147 offset:34816
	ds_read_b128 v[196:199], v147 offset:35840
	ds_read_b128 v[228:231], v147 offset:36864
	ds_read_b128 v[232:235], v147 offset:37888
	ds_read_b128 v[236:239], v147 offset:38912
	ds_read_b128 v[240:243], v147 offset:39936
	global_load_lds_dwordx4 v[250:251], off
	v_lshl_add_u64 v[250:251], s[28:29], 0, v[132:133]
	s_mov_b32 m0, s70
	s_nop 0
	global_load_lds_dwordx4 v[250:251], off
	s_waitcnt vmcnt(8)
	s_waitcnt lgkmcnt(0)
	s_barrier
	s_waitcnt lgkmcnt(0)
	v_mfma_f32_16x16x32_bf16 v[126:129], v[140:143], v[176:179], v[126:129]
	v_mfma_f32_16x16x32_bf16 v[122:125], v[152:155], v[176:179], v[122:125]
	v_mfma_f32_16x16x32_bf16 v[110:113], v[140:143], v[184:187], v[110:113]
	v_mfma_f32_16x16x32_bf16 v[106:109], v[152:155], v[184:187], v[106:109]
	v_mfma_f32_16x16x32_bf16 v[94:97], v[140:143], v[228:231], v[94:97]
	v_mfma_f32_16x16x32_bf16 v[90:93], v[152:155], v[228:231], v[90:93]
	v_mfma_f32_16x16x32_bf16 v[78:81], v[140:143], v[236:239], v[78:81]
	v_mfma_f32_16x16x32_bf16 v[74:77], v[152:155], v[236:239], v[74:77]
	v_mfma_f32_16x16x32_bf16 v[126:129], v[148:151], v[180:183], v[126:129]
	v_mfma_f32_16x16x32_bf16 v[122:125], v[156:159], v[180:183], v[122:125]
	v_mfma_f32_16x16x32_bf16 v[110:113], v[148:151], v[196:199], v[110:113]
	v_mfma_f32_16x16x32_bf16 v[106:109], v[156:159], v[196:199], v[106:109]
	v_mfma_f32_16x16x32_bf16 v[94:97], v[148:151], v[232:235], v[94:97]
	v_mfma_f32_16x16x32_bf16 v[90:93], v[156:159], v[232:235], v[90:93]
	v_mfma_f32_16x16x32_bf16 v[78:81], v[148:151], v[240:243], v[78:81]
	v_mfma_f32_16x16x32_bf16 v[74:77], v[156:159], v[240:243], v[74:77]
	v_mfma_f32_16x16x32_bf16 v[118:121], v[160:163], v[176:179], v[118:121]
	v_mfma_f32_16x16x32_bf16 v[114:117], v[168:171], v[176:179], v[114:117]
	v_mfma_f32_16x16x32_bf16 v[102:105], v[160:163], v[184:187], v[102:105]
	v_mfma_f32_16x16x32_bf16 v[98:101], v[168:171], v[184:187], v[98:101]
	v_mfma_f32_16x16x32_bf16 v[86:89], v[160:163], v[228:231], v[86:89]
	v_mfma_f32_16x16x32_bf16 v[82:85], v[168:171], v[228:231], v[82:85]
	v_mfma_f32_16x16x32_bf16 v[70:73], v[160:163], v[236:239], v[70:73]
	v_mfma_f32_16x16x32_bf16 v[66:69], v[168:171], v[236:239], v[66:69]
	v_mfma_f32_16x16x32_bf16 v[118:121], v[164:167], v[180:183], v[118:121]
	v_mfma_f32_16x16x32_bf16 v[114:117], v[172:175], v[180:183], v[114:117]
	v_mfma_f32_16x16x32_bf16 v[102:105], v[164:167], v[196:199], v[102:105]
	v_mfma_f32_16x16x32_bf16 v[98:101], v[172:175], v[196:199], v[98:101]
	v_mfma_f32_16x16x32_bf16 v[86:89], v[164:167], v[232:235], v[86:89]
	v_mfma_f32_16x16x32_bf16 v[82:85], v[172:175], v[232:235], v[82:85]
	v_mfma_f32_16x16x32_bf16 v[70:73], v[164:167], v[240:243], v[70:73]
	v_mfma_f32_16x16x32_bf16 v[66:69], v[172:175], v[240:243], v[66:69]
	s_barrier
; #define PG8_STAGE(bufoff, gbase, voff) do { _Pragma("unroll") for (int _i = 0; _i < 2; ++_i) \
;         __builtin_amdgcn_global_load_lds((const unsigned*)((const char*)(gbase) + (voff)[_i]), (PG8_LAS unsigned*)(lds + (bufoff) + ldsw + _i * 8192), 16, 0, 0); } while (0)
; #define PG8_LDA(dst, b, h) do { _Pragma("unroll") for (int m = 0; m < 4; ++m) _Pragma("unroll") for (int k = 0; k < 2; ++k) dst[m][k] = *(const PG8_LAS bf16x8*)(lds + PG8_SA(b, h) + aoff + m * 2048 + k * 1024); } while (0)
; #define PG8_MMA(ai, bj, At, Bt) do { __builtin_amdgcn_s_setprio(1); _Pragma("unroll") for (int m = 0; m < 4; ++m) _Pragma("unroll") for (int n = 0; n < 2; ++n) _Pragma("unroll") for (int k = 0; k < 2; ++k) \
;         acc[ai][bj][m][n] = __builtin_amdgcn_mfma_f32_16x16x32_bf16(Bt[n][k], At[m][k], acc[ai][bj][m][n], 0, 0, 0); __builtin_amdgcn_s_setprio(0); } while (0)
; #define PG8_WAIT_V(n) asm volatile("s_waitcnt vmcnt(" #n ")" ::: "memory")
; #define PG8_WAIT_L(n) asm volatile("s_waitcnt lgkmcnt(" #n ")" ::: "memory")
; #define PG8_BAR __builtin_amdgcn_s_barrier()
; #define PG8_SCHED __builtin_amdgcn_sched_barrier(0)
; template <class Epi, class Sched, bool ALIGN_EPI = false, bool SP2 = false>
; __device__ __forceinline__ void gemm_phase(PG8_LAS unsigned char* lds, const Gemm g, const Sched& S, const Epi& E, int tid_in) {
;     ...
;             PG8_LDA(At, 1, 1); PG8_STAGE(PG8_SB(1, 0), b3, voffB); PG8_STAGE(PG8_SB(1, 1), b3 + hstep, voffB); PG8_STAGE(PG8_SA(1, 0), a3, voffA);
;             PG8_WAIT_V(8); PG8_WAIT_L(0); PG8_BAR; PG8_MMA(1, 0, At, B0); PG8_MMA(1, 1, At, B1); PG8_BAR; PG8_SCHED;
;     ...
;         if constexpr (ALIGN_EPI) { if (wr == 0) PG8_BAR; }
	s_add_i32 s28, s62, s41
	v_lshl_add_u64 v[218:219], v[218:219], 0, s[54:55]
	s_mov_b32 m0, s28
	ds_read_b128 v[176:179], v147 offset:49152
	ds_read_b128 v[180:183], v147 offset:50176
	ds_read_b128 v[184:187], v147 offset:51200
	ds_read_b128 v[196:199], v147 offset:52224
	ds_read_b128 v[228:231], v147 offset:53248
	ds_read_b128 v[232:235], v147 offset:54272
	ds_read_b128 v[236:239], v147 offset:55296
	ds_read_b128 v[240:243], v147 offset:56320
	global_load_lds_dwordx4 v[218:219], off
	s_add_i32 m0, s28, 0x2000
	s_add_u32 s26, s26, 0x40080
	v_lshl_add_u64 v[218:219], v[244:245], 0, s[54:55]
	s_addc_u32 s27, s27, 0
	s_add_i32 s28, s63, s41
	global_load_lds_dwordx4 v[218:219], off
	v_lshl_add_u64 v[218:219], s[26:27], 0, v[0:1]
	s_mov_b32 m0, s28
	s_nop 0
	global_load_lds_dwordx4 v[218:219], off
	v_lshl_add_u64 v[218:219], s[26:27], 0, v[134:135]
	s_add_i32 m0, s28, 0x2000
	s_nop 0
	global_load_lds_dwordx4 v[218:219], off
	v_lshl_add_u64 v[218:219], v[246:247], 0, s[54:55]
	s_mov_b32 m0, s71
	s_nop 0
	global_load_lds_dwordx4 v[218:219], off
	v_lshl_add_u64 v[218:219], v[248:249], 0, s[54:55]
	s_mov_b32 m0, s72
	s_nop 0
	global_load_lds_dwordx4 v[218:219], off
	s_waitcnt vmcnt(8)
	s_waitcnt lgkmcnt(0)
	s_barrier
	s_waitcnt lgkmcnt(0)
	v_mfma_f32_16x16x32_bf16 v[62:65], v[140:143], v[176:179], v[62:65]
	v_mfma_f32_16x16x32_bf16 v[58:61], v[152:155], v[176:179], v[58:61]
	v_mfma_f32_16x16x32_bf16 v[46:49], v[140:143], v[184:187], v[46:49]
	v_mfma_f32_16x16x32_bf16 v[42:45], v[152:155], v[184:187], v[42:45]
	v_mfma_f32_16x16x32_bf16 v[30:33], v[140:143], v[228:231], v[30:33]
	v_mfma_f32_16x16x32_bf16 v[26:29], v[152:155], v[228:231], v[26:29]
	v_mfma_f32_16x16x32_bf16 v[14:17], v[140:143], v[236:239], v[14:17]
	v_mfma_f32_16x16x32_bf16 v[10:13], v[152:155], v[236:239], v[10:13]
	v_mfma_f32_16x16x32_bf16 v[62:65], v[148:151], v[180:183], v[62:65]
	v_mfma_f32_16x16x32_bf16 v[58:61], v[156:159], v[180:183], v[58:61]
	v_mfma_f32_16x16x32_bf16 v[46:49], v[148:151], v[196:199], v[46:49]
	v_mfma_f32_16x16x32_bf16 v[42:45], v[156:159], v[196:199], v[42:45]
	v_mfma_f32_16x16x32_bf16 v[30:33], v[148:151], v[232:235], v[30:33]
	v_mfma_f32_16x16x32_bf16 v[26:29], v[156:159], v[232:235], v[26:29]
	v_mfma_f32_16x16x32_bf16 v[14:17], v[148:151], v[240:243], v[14:17]
	v_mfma_f32_16x16x32_bf16 v[10:13], v[156:159], v[240:243], v[10:13]
	v_mfma_f32_16x16x32_bf16 v[54:57], v[160:163], v[176:179], v[54:57]
	v_mfma_f32_16x16x32_bf16 v[50:53], v[168:171], v[176:179], v[50:53]
	v_mfma_f32_16x16x32_bf16 v[38:41], v[160:163], v[184:187], v[38:41]
	v_mfma_f32_16x16x32_bf16 v[34:37], v[168:171], v[184:187], v[34:37]
	v_mfma_f32_16x16x32_bf16 v[22:25], v[160:163], v[228:231], v[22:25]
	v_mfma_f32_16x16x32_bf16 v[18:21], v[168:171], v[228:231], v[18:21]
	v_mfma_f32_16x16x32_bf16 v[6:9], v[160:163], v[236:239], v[6:9]
	v_mfma_f32_16x16x32_bf16 v[2:5], v[168:171], v[236:239], v[2:5]
	v_mfma_f32_16x16x32_bf16 v[54:57], v[164:167], v[180:183], v[54:57]
	v_mfma_f32_16x16x32_bf16 v[50:53], v[172:175], v[180:183], v[50:53]
	v_mfma_f32_16x16x32_bf16 v[38:41], v[164:167], v[196:199], v[38:41]
	v_mfma_f32_16x16x32_bf16 v[34:37], v[172:175], v[196:199], v[34:37]
	v_mfma_f32_16x16x32_bf16 v[22:25], v[164:167], v[232:235], v[22:25]
	v_mfma_f32_16x16x32_bf16 v[18:21], v[172:175], v[232:235], v[18:21]
	v_mfma_f32_16x16x32_bf16 v[6:9], v[164:167], v[240:243], v[6:9]
	v_mfma_f32_16x16x32_bf16 v[2:5], v[172:175], v[240:243], v[2:5]
	s_barrier
	s_add_i32 s78, s78, 2
	s_add_u32 s24, s24, 0x100
	s_addc_u32 s25, s25, 0
	s_add_u32 s76, s76, 0x100
	s_addc_u32 s77, s77, 0
	s_cmp_gt_u32 s78, 13
	s_cbranch_scc0 .LBB0_679
	s_setprio 0
	s_and_b64 vcc, exec, s[12:13]
	s_cbranch_vccz .LBB0_682
	s_barrier
